# P8/P9 GEMM prologue: both pipeline-fill LDS-DMA batches issued together (one exposed latency instead of two)
# speedup vs baseline: 1.0079x; 1.0079x over previous
; #define PG8_STAGE(bufoff, gbase) PG8_STAGE_(bufoff, gbase, voffA)
; #define PG8_STAGEB(bufoff, gbase) PG8_STAGE_(bufoff, gbase, voffB)
; #define PG8_WAIT_V(n) asm volatile("s_waitcnt vmcnt(" #n ")" ::: "memory")
; #define PG8_BAR __builtin_amdgcn_s_barrier()
; template <class Epi>
; __device__ __forceinline__ void gemm_phase(LAS unsigned char* lds, const Gemm g, const StaticOrder& S, const Epi& E) {
;     ...
;     const char* cA = (const char*)g.A + (size_t)cur.pm * tstep; const char* cB = (const char*)g.Bt + (size_t)cur.pn * tstep;
;     PG8_STAGEB(PG8_SB(0, 0), cB); PG8_STAGE(PG8_SA(0, 0), cA); PG8_STAGEB(PG8_SB(0, 1), cB + hstep); PG8_STAGE(PG8_SA(0, 1), cA + hstep);
;     if (wr == 1) PG8_BAR;
;     PG8_WAIT_V(4); PG8_BAR;
;     PG8_STAGEB(PG8_SB(1, 0), cB + kstep); PG8_STAGE(PG8_SA(1, 0), cA + kstep); PG8_STAGEB(PG8_SB(1, 1), cB + hstep + kstep);
;     PG8_WAIT_V(6); PG8_BAR;
.LBB0_1366:
	s_or_b64 exec, exec, s[0:1]
	v_readlane_b32 s0, v255, 46
	v_readlane_b32 s1, v255, 47
	s_lshl_b32 s59, s0, 23
	s_mov_b64 s[0:1], s[94:95]
	v_mov_b32_e32 v0, v250
	s_waitcnt lgkmcnt(0)
	s_barrier
	s_and_b64 vcc, exec, s[82:83]
	v_readfirstlane_b32 s20, v0
	s_cbranch_vccnz .LBB0_1384
	v_lshlrev_b32_e32 v2, 4, v0
	v_add_u32_e32 v3, 0x2000, v2
	v_ashrrev_i32_e32 v4, 31, v3
	v_lshrrev_b32_e32 v4, 22, v4
	v_add_u32_e32 v4, v3, v4
	v_ashrrev_i32_e32 v10, 10, v4
	v_mul_i32_i24_e32 v4, 0x400, v10
	v_sub_u32_e32 v3, v3, v4
	v_lshrrev_b32_e32 v4, 4, v3
	v_bitop3_b32 v3, v4, v3, 32 bitop3:0x6c
	v_ashrrev_i32_e32 v4, 31, v3
	v_lshrrev_b32_e32 v4, 26, v4
	v_add_u32_e32 v4, v3, v4
	v_lshlrev_b32_e32 v5, 3, v10
	v_ashrrev_i32_e32 v11, 6, v4
	v_and_b32_e32 v5, -16, v5
	v_add_u32_e32 v5, v11, v5
	v_and_b32_e32 v6, 3, v11
	s_mov_b32 s4, 0xfffe0
	v_lshrrev_b32_e32 v7, 2, v5
	v_lshlrev_b32_e32 v8, 1, v5
	v_and_or_b32 v6, v5, s4, v6
	v_and_b32_e32 v7, 4, v7
	v_and_b32_e32 v8, 24, v8
	v_and_b32_e32 v4, 0xc0, v4
	v_or3_b32 v6, v6, v7, v8
	v_sub_u32_e32 v3, v3, v4
	v_mov_b32_e32 v8, 1
	v_lshlrev_b32_e32 v7, 5, v10
	v_ashrrev_i16_sdwa v3, v8, sext(v3) dst_sel:DWORD dst_unused:UNUSED_PAD src0_sel:DWORD src1_sel:BYTE_0
	v_and_b32_e32 v7, 32, v7
	v_bfe_i32 v12, v3, 0, 16
	v_add_lshl_u32 v3, v7, v12, 1
	v_lshl_add_u32 v140, v6, 12, v3
	v_lshl_add_u32 v142, v5, 12, v3
	v_bfe_i32 v3, v0, 27, 1
	v_lshrrev_b32_e32 v3, 22, v3
	v_add_u32_e32 v3, v2, v3
	v_and_b32_e32 v3, 0xfffffc00, v3
	v_sub_u32_e32 v2, v2, v3
	v_lshrrev_b32_e32 v3, 4, v2
	v_bitop3_b32 v3, v3, v2, 32 bitop3:0x6c
	v_ashrrev_i32_e32 v2, 31, v2
	v_lshrrev_b32_e32 v2, 26, v2
	v_add_u32_e32 v2, v3, v2
	s_load_dwordx2 s[0:1], s[0:1], 0xf0
	v_ashrrev_i32_e32 v13, 6, v2
	v_ashrrev_i32_e32 v2, 31, v0
	v_lshrrev_b32_e32 v2, 26, v2
	v_add_u32_e32 v2, v0, v2
	v_ashrrev_i32_e32 v14, 6, v2
	v_lshlrev_b32_e32 v2, 3, v14
	s_waitcnt lgkmcnt(0)
	s_add_u32 s81, s0, 0x39be1800
	v_and_b32_e32 v2, -16, v2
	s_addc_u32 s82, s1, 0
	v_add_u32_e32 v2, v13, v2
	s_add_u32 s6, s0, s59
	v_and_b32_e32 v4, 3, v13
	v_lshrrev_b32_e32 v5, 2, v2
	v_lshlrev_b32_e32 v6, 1, v2
	s_addc_u32 s7, s1, 0
	v_and_or_b32 v4, v2, s4, v4
	v_and_b32_e32 v5, 4, v5
	v_and_b32_e32 v6, 24, v6
	s_add_u32 s83, s6, 0x11400000
	v_or3_b32 v4, v4, v5, v6
	v_mul_i32_i24_e32 v6, 64, v13
	s_addc_u32 s84, s7, 0
	s_ashr_i32 s24, s20, 6
	v_sub_u32_e32 v3, v3, v6
	s_ashr_i32 s25, s20, 8
	s_lshl_b32 s85, s24, 10
	v_lshlrev_b32_e32 v5, 5, v14
	v_ashrrev_i16_sdwa v3, v8, sext(v3) dst_sel:DWORD dst_unused:UNUSED_PAD src0_sel:DWORD src1_sel:BYTE_0
	v_readlane_b32 s6, v254, 37
	v_and_b32_e32 v5, 32, v5
	v_bfe_i32 v15, v3, 0, 16
	v_readlane_b32 s7, v254, 38
	s_add_u32 s6, s83, s6
	v_add_lshl_u32 v3, v5, v15, 1
	s_addc_u32 s7, s84, s7
	s_add_i32 s38, s85, 0
	v_lshl_add_u32 v144, v4, 12, v3
	s_add_i32 m0, s38, 0x10000
	s_mov_b32 s23, s20
	global_load_lds_dwordx4 v144, s[6:7]
	s_add_i32 m0, s38, 0x12000
	v_readlane_b32 s20, v254, 52
	v_readlane_b32 s21, v254, 53
	s_add_u32 s20, s81, s20
	v_lshl_add_u32 v156, v2, 12, v3
	global_load_lds_dwordx4 v140, s[6:7]
	s_addc_u32 s21, s82, s21
	s_mov_b32 m0, s38
	s_add_i32 s80, s38, 0x2000
	global_load_lds_dwordx4 v156, s[20:21]
	s_mov_b32 m0, s80
	s_add_u32 s30, s6, 0x80000
	global_load_lds_dwordx4 v142, s[20:21]
	s_addc_u32 s31, s7, 0
	s_add_i32 m0, s38, 0x14000
	v_mov_b32_e32 v145, v1
	global_load_lds_dwordx4 v144, s[30:31]
	s_add_i32 m0, s38, 0x16000
	v_mov_b32_e32 v141, v1
	global_load_lds_dwordx4 v140, s[30:31]
	s_add_u32 s30, s20, 0x80000
	s_addc_u32 s31, s21, 0
	s_add_i32 s86, s38, 0x4000
	s_mov_b32 m0, s86
	s_add_i32 s87, s38, 0x6000
	global_load_lds_dwordx4 v156, s[30:31]
	s_mov_b32 m0, s87
	v_mov_b32_e32 v157, v1
	global_load_lds_dwordx4 v142, s[30:31]
	v_mov_b32_e32 v143, v1
	v_lshl_add_u64 v[8:9], s[6:7], 0, v[144:145]
	v_lshl_add_u64 v[6:7], s[6:7], 0, v[140:141]
	v_lshl_add_u64 v[4:5], s[20:21], 0, v[156:157]
	s_add_i32 m0, s38, 0x17f80
	s_nop 0
	global_load_lds_dwordx4 v144, s[6:7] offset:128
	s_add_i32 m0, s38, 0x19f80
	s_nop 0
	global_load_lds_dwordx4 v140, s[6:7] offset:128
	s_add_i32 m0, s38, 0x7f80
	s_nop 0
	global_load_lds_dwordx4 v156, s[20:21] offset:128
	s_add_i32 m0, s38, 0x9f80
	s_nop 0
	global_load_lds_dwordx4 v142, s[20:21] offset:128
	s_add_u32 s100, s6, 0x80080
	s_addc_u32 s101, s7, 0
	s_add_i32 m0, s38, 0x1c000
	s_nop 0
	global_load_lds_dwordx4 v144, s[100:101]
	s_add_i32 m0, s38, 0x1e000
	s_nop 0
	global_load_lds_dwordx4 v140, s[100:101]
	s_cmp_lg_u32 s25, 1
	v_lshl_add_u64 v[2:3], s[20:21], 0, v[142:143]
	s_cbranch_scc1 .LBB0_1369
	s_barrier
.LBB0_1369:
	s_add_u32 s46, s0, 0x17b00000
	s_addc_u32 s47, s1, 0
	s_add_u32 s48, s0, 0x3bbe1800
	s_addc_u32 s49, s1, 0
	s_lshl_b32 s24, s24, 12
	s_add_i32 m0, s38, 0x18000
	v_lshl_add_u64 v[8:9], v[8:9], 0, s[16:17]
	s_lshl_b32 s30, s25, 13
	s_and_b32 s31, s24, 0x3000
	s_waitcnt vmcnt(10)
	s_barrier
	v_lshl_add_u64 v[6:7], v[6:7], 0, s[16:17]
	s_add_i32 m0, s38, 0x1a000
	s_add_i32 s88, s38, 0x8000
	s_add_i32 s89, s38, 0xa000
	v_lshl_add_u64 v[4:5], v[4:5], 0, s[16:17]
	s_mov_b32 m0, s88
	s_add_u32 s24, s6, 0x80080
	v_lshl_add_u64 v[2:3], v[2:3], 0, s[16:17]
	s_mov_b32 m0, s89
	s_addc_u32 s25, s7, 0
	s_add_i32 m0, s38, 0x1c000
	v_lshl_add_u64 v[2:3], s[24:25], 0, v[144:145]
	v_lshl_add_u64 v[2:3], s[24:25], 0, v[140:141]
	s_add_i32 m0, s38, 0x1e000
	v_readlane_b32 s24, v254, 50
	v_and_b32_e32 v2, 15, v0
	v_and_b32_e32 v3, 48, v0
	v_lshlrev_b32_e32 v0, 2, v0
	v_lshlrev_b32_e32 v2, 6, v2
	v_and_b32_e32 v0, 32, v0
	v_or_b32_e32 v4, v2, v3
	v_bitop3_b32 v2, v2, v0, v3 bitop3:0x36
	v_or_b32_e32 v162, s31, v2
	v_lshlrev_b32_e32 v2, 15, v14
	v_and_b32_e32 v2, 0xffff0000, v2
	v_lshl_add_u32 v2, v13, 12, v2
	v_and_b32_e32 v3, 1, v14
	v_lshl_or_b32 v2, v3, 6, v2
	v_lshl_add_u32 v158, v15, 1, v2
	v_lshlrev_b32_e32 v2, 15, v10
	v_and_b32_e32 v2, 0xffff0000, v2
	s_waitcnt vmcnt(6)
	v_lshl_add_u32 v2, v11, 12, v2
	v_and_b32_e32 v3, 1, v10
	v_bitop3_b32 v0, v4, s30, v0 bitop3:0xde
	v_lshl_or_b32 v2, v3, 6, v2
	v_mov_b32_e32 v159, v1
	v_lshl_add_u32 v160, v12, 1, v2
	v_mov_b32_e32 v161, v1
	s_mov_b32 s90, 0
	v_add_u32_e32 v163, 0, v0
	v_readlane_b32 s34, v254, 36
	s_mov_b32 s35, s24
	s_movk_i32 s4, 0x7000
	s_barrier
	v_readlane_b32 s25, v254, 51
	s_branch .LBB0_1371

; __device__ __forceinline__ int fresh_tid() { int t = threadIdx.x; asm volatile("" : "+v"(t)); return t; }
; #define PG8_STAGE(bufoff, gbase) PG8_STAGE_(bufoff, gbase, voffA)
; #define PG8_STAGEB(bufoff, gbase) PG8_STAGE_(bufoff, gbase, voffB)
; #define PG8_WAIT_V(n) asm volatile("s_waitcnt vmcnt(" #n ")" ::: "memory")
; #define PG8_BAR __builtin_amdgcn_s_barrier()
; template <class Epi>
; __device__ __forceinline__ void gemm_phase(LAS unsigned char* lds, const Gemm g, const StaticOrder& S, const Epi& E) {
;     const int tid = fresh_tid(), wid = __builtin_amdgcn_readfirstlane(tid >> 6), lane = tid & 63, wr = wid >> 2, wc = wid & 3, fr = lane & 15, fq = lane >> 4;
;     const int K = g.K, nt = K / BK;
;     unsigned voffA[2], voffB[2];
; #pragma unroll
;     for (int i = 0; i < 2; ++i) { int R, C; stage_rc(tid * 16 + i * 8192, R, C); const int Rb = Epi::PERM ? ((R & ~31) + perm32(R & 31)) : R;
;         voffA[i] = (unsigned)(R * K + C) * 2u; voffB[i] = (unsigned)(Rb * K + C) * 2u; }
;     const size_t kstep = (size_t)(BK * 2);
;     const size_t hstep = (size_t)HALF * K * 2;
;     const size_t tstep = 2 * hstep;
;     const unsigned ldsw = (unsigned)wid * 1024u;
;     const int aoff = lds_byte(wr * 64 + fr, fq * 8), boff = lds_byte(wc * 32 + fr, fq * 8);
;     ...
;     Unit cur, nxt; int ui = 0;
;     if (!S.next(0, cur)) return;
;     f32x4 acc[2][2][4][2];
; #pragma unroll
;     for (int a = 0; a < 2; ++a)
; #pragma unroll
;         for (int b = 0; b < 2; ++b)
; #pragma unroll
;             for (int m = 0; m < 4; ++m)
; #pragma unroll
;                 for (int n = 0; n < 2; ++n) acc[a][b][m][n] = (f32x4){0.f, 0.f, 0.f, 0.f};
;     bf16x8 At[4][2], B0[2][2], B1[2][2];
;     const char* cA = (const char*)g.A + (size_t)cur.pm * tstep; const char* cB = (const char*)g.Bt + (size_t)cur.pn * tstep;
;     PG8_STAGEB(PG8_SB(0, 0), cB); PG8_STAGE(PG8_SA(0, 0), cA); PG8_STAGEB(PG8_SB(0, 1), cB + hstep); PG8_STAGE(PG8_SA(0, 1), cA + hstep);
;     if (wr == 1) PG8_BAR;
;     PG8_WAIT_V(4); PG8_BAR;
;     PG8_STAGEB(PG8_SB(1, 0), cB + kstep); PG8_STAGE(PG8_SA(1, 0), cA + kstep); PG8_STAGEB(PG8_SB(1, 1), cB + hstep + kstep);
;     PG8_WAIT_V(6); PG8_BAR;
.LBB0_1436:
	s_or_b64 exec, exec, s[0:1]
	s_mov_b64 s[0:1], s[94:95]
	s_waitcnt lgkmcnt(0)
	v_mov_b32_e32 v2, v250
	s_barrier
	s_and_b64 vcc, exec, s[82:83]
	v_readfirstlane_b32 s38, v2
	s_cbranch_vccnz .LBB0_1452
	v_lshlrev_b32_e32 v0, 4, v2
	v_add_u32_e32 v4, 0x2000, v0
	v_ashrrev_i32_e32 v3, 31, v4
	v_lshrrev_b32_e32 v3, 22, v3
	v_add_u32_e32 v3, v4, v3
	v_ashrrev_i32_e32 v3, 10, v3
	v_mul_i32_i24_e32 v5, 0x400, v3
	v_sub_u32_e32 v4, v4, v5
	v_lshrrev_b32_e32 v5, 4, v4
	v_bitop3_b32 v5, v5, v4, 32 bitop3:0x6c
	v_ashrrev_i32_e32 v4, 31, v5
	v_lshrrev_b32_e32 v4, 26, v4
	v_add_u32_e32 v6, v5, v4
	v_lshlrev_b32_e32 v7, 3, v3
	v_ashrrev_i32_e32 v4, 6, v6
	v_and_b32_e32 v7, -16, v7
	v_add_u32_e32 v7, v4, v7
	v_and_b32_e32 v8, 3, v4
	s_mov_b32 s4, 0xfffe0
	v_lshrrev_b32_e32 v9, 2, v7
	v_lshlrev_b32_e32 v10, 1, v7
	v_and_b32_e32 v6, 0xc0, v6
	v_and_or_b32 v8, v7, s4, v8
	v_and_b32_e32 v9, 4, v9
	v_and_b32_e32 v10, 24, v10
	v_sub_u32_e32 v5, v5, v6
	v_mov_b32_e32 v12, 1
	v_or3_b32 v8, v8, v9, v10
	v_lshlrev_b32_e32 v9, 5, v3
	v_ashrrev_i16_sdwa v5, v12, sext(v5) dst_sel:DWORD dst_unused:UNUSED_PAD src0_sel:DWORD src1_sel:BYTE_0
	v_and_b32_e32 v9, 32, v9
	v_bfe_i32 v5, v5, 0, 16
	v_add_lshl_u32 v6, v9, v5, 1
	v_lshl_add_u32 v130, v8, 12, v6
	v_lshl_add_u32 v132, v7, 12, v6
	v_bfe_i32 v6, v2, 27, 1
	v_lshrrev_b32_e32 v6, 22, v6
	v_add_u32_e32 v6, v0, v6
	v_and_b32_e32 v6, 0xfffffc00, v6
	v_sub_u32_e32 v0, v0, v6
	v_lshrrev_b32_e32 v6, 4, v0
	v_bitop3_b32 v8, v6, v0, 32 bitop3:0x6c
	v_ashrrev_i32_e32 v0, 31, v0
	v_lshrrev_b32_e32 v0, 26, v0
	v_readlane_b32 s6, v255, 48
	v_add_u32_e32 v0, v8, v0
	v_readlane_b32 s7, v255, 49
	s_load_dwordx4 s[44:47], s[0:1], 0xe8
	v_ashrrev_i32_e32 v6, 6, v0
	v_ashrrev_i32_e32 v0, 31, v2
	s_and_b64 s[6:7], s[6:7], exec
	v_lshrrev_b32_e32 v0, 26, v0
	s_cselect_b32 s6, 0, 0xe8
	v_add_u32_e32 v0, v2, v0
	s_add_u32 s0, s0, s6
	v_ashrrev_i32_e32 v7, 6, v0
	s_addc_u32 s1, s1, 0
	v_lshlrev_b32_e32 v0, 3, v7
	s_waitcnt lgkmcnt(0)
	s_add_u32 s50, s46, 0x3bbe1800
	v_and_b32_e32 v0, -16, v0
	s_addc_u32 s51, s47, 0
	v_add_u32_e32 v9, v6, v0
	s_add_u32 s6, s46, s59
	v_and_b32_e32 v0, 3, v6
	v_lshrrev_b32_e32 v10, 2, v9
	v_lshlrev_b32_e32 v11, 1, v9
	s_addc_u32 s7, s47, 0
	v_and_or_b32 v0, v9, s4, v0
	v_and_b32_e32 v10, 4, v10
	v_and_b32_e32 v11, 24, v11
	s_add_u32 s52, s6, 0x13400000
	v_or3_b32 v0, v0, v10, v11
	v_mul_i32_i24_e32 v11, 64, v6
	s_addc_u32 s53, s7, 0
	s_ashr_i32 s6, s38, 6
	v_sub_u32_e32 v8, v8, v11
	s_ashr_i32 s7, s38, 8
	s_lshl_b32 s54, s6, 10
	v_lshlrev_b32_e32 v10, 5, v7
	v_ashrrev_i16_sdwa v8, v12, sext(v8) dst_sel:DWORD dst_unused:UNUSED_PAD src0_sel:DWORD src1_sel:BYTE_0
	v_readlane_b32 s20, v254, 37
	v_and_b32_e32 v10, 32, v10
	v_bfe_i32 v8, v8, 0, 16
	v_readlane_b32 s21, v254, 38
	s_add_u32 s20, s52, s20
	v_add_lshl_u32 v10, v10, v8, 1
	s_addc_u32 s21, s53, s21
	s_add_i32 s55, s54, 0
	v_lshl_add_u32 v0, v0, 12, v10
	s_add_i32 m0, s55, 0x10000
	v_readlane_b32 s24, v254, 52
	global_load_lds_dwordx4 v0, s[20:21]
	s_add_i32 m0, s55, 0x12000
	v_readlane_b32 s25, v254, 53
	s_add_u32 s30, s50, s24
	v_lshl_add_u32 v134, v9, 12, v10
	global_load_lds_dwordx4 v130, s[20:21]
	s_addc_u32 s31, s51, s25
	s_mov_b32 m0, s55
	s_add_i32 s62, s55, 0x2000
	global_load_lds_dwordx4 v134, s[30:31]
	s_mov_b32 m0, s62
	s_add_u32 s24, s20, 0x80000
	global_load_lds_dwordx4 v132, s[30:31]
	s_addc_u32 s25, s21, 0
	s_add_i32 m0, s55, 0x14000
	s_load_dwordx2 s[0:1], s[0:1], 0x0
	global_load_lds_dwordx4 v0, s[24:25]
	s_add_i32 m0, s55, 0x16000
	s_nop 0
	global_load_lds_dwordx4 v130, s[24:25]
	s_add_u32 s24, s30, 0x80000
	s_addc_u32 s25, s31, 0
	s_add_i32 s63, s55, 0x4000
	s_mov_b32 m0, s63
	s_add_i32 s66, s55, 0x6000
	global_load_lds_dwordx4 v134, s[24:25]
	s_mov_b32 m0, s66
	s_nop 0
	global_load_lds_dwordx4 v132, s[24:25]
	s_add_i32 m0, s55, 0x17f80
	s_nop 0
	global_load_lds_dwordx4 v0, s[20:21] offset:128
	s_add_i32 m0, s55, 0x19f80
	s_nop 0
	global_load_lds_dwordx4 v130, s[20:21] offset:128
	s_add_i32 m0, s55, 0x7f80
	s_nop 0
	global_load_lds_dwordx4 v134, s[30:31] offset:128
	s_add_i32 m0, s55, 0x9f80
	s_nop 0
	global_load_lds_dwordx4 v132, s[30:31] offset:128
	s_add_u32 s100, s20, 0x80080
	s_addc_u32 s101, s21, 0
	s_add_i32 m0, s55, 0x1c000
	s_nop 0
	global_load_lds_dwordx4 v0, s[100:101]
	s_add_i32 m0, s55, 0x1e000
	s_nop 0
	global_load_lds_dwordx4 v130, s[100:101]
	s_cmp_lg_u32 s7, 1
	s_cbranch_scc1 .LBB0_1439
	s_barrier
.LBB0_1439:
	v_lshl_add_u64 v[10:11], s[20:21], 0, v[0:1]
	v_mov_b32_e32 v131, v1
	v_lshl_add_u64 v[12:13], s[20:21], 0, v[130:131]
	v_mov_b32_e32 v135, v1
	s_lshl_b32 s6, s6, 12
	s_add_i32 m0, s55, 0x18000
	v_lshl_add_u64 v[10:11], v[10:11], 0, s[16:17]
	v_lshl_add_u64 v[14:15], s[30:31], 0, v[134:135]
	v_mov_b32_e32 v133, v1
	s_lshl_b32 s24, s7, 13
	s_and_b32 s25, s6, 0x3000
	s_waitcnt vmcnt(10)
	s_barrier
	v_lshl_add_u64 v[10:11], v[12:13], 0, s[16:17]
	s_add_i32 m0, s55, 0x1a000
	s_add_i32 s67, s55, 0x8000
	s_add_i32 s80, s55, 0xa000
	v_lshl_add_u64 v[16:17], s[30:31], 0, v[132:133]
	v_lshl_add_u64 v[10:11], v[14:15], 0, s[16:17]
	s_mov_b32 m0, s67
	s_add_u32 s6, s20, 0x80080
	v_lshl_add_u64 v[10:11], v[16:17], 0, s[16:17]
	s_mov_b32 m0, s80
	s_addc_u32 s7, s21, 0
	s_add_i32 m0, s55, 0x1c000
	v_lshl_add_u64 v[10:11], s[6:7], 0, v[0:1]
	v_lshl_add_u64 v[10:11], s[6:7], 0, v[130:131]
	s_add_i32 m0, s55, 0x1e000
	v_and_b32_e32 v9, 15, v2
	v_and_b32_e32 v10, 48, v2
	v_lshlrev_b32_e32 v2, 2, v2
	v_lshlrev_b32_e32 v9, 6, v9
	v_and_b32_e32 v2, 32, v2
	v_or_b32_e32 v11, v9, v10
	v_bitop3_b32 v9, v9, v2, v10 bitop3:0x36
	v_or_b32_e32 v142, s25, v9
	v_lshlrev_b32_e32 v9, 15, v7
	v_and_b32_e32 v9, 0xffff0000, v9
	v_lshl_add_u32 v6, v6, 12, v9
	v_and_b32_e32 v7, 1, v7
	v_lshl_or_b32 v6, v7, 6, v6
	v_lshl_add_u32 v136, v8, 1, v6
	v_lshlrev_b32_e32 v6, 15, v3
	v_and_b32_e32 v6, 0xffff0000, v6
	s_waitcnt vmcnt(6)
	v_lshl_add_u32 v4, v4, 12, v6
	v_and_b32_e32 v3, 1, v3
	v_bitop3_b32 v2, v11, s24, v2 bitop3:0xde
	v_lshl_or_b32 v3, v3, 6, v4
	v_readlane_b32 s6, v254, 50
	v_mov_b32_e32 v137, v1
	v_lshl_add_u32 v138, v5, 1, v3
	v_mov_b32_e32 v139, v1
	s_mov_b32 s81, 0
	v_add_u32_e32 v143, 0, v2
	v_readlane_b32 s82, v254, 36
	s_mov_b32 s83, s6
	s_barrier
	v_readlane_b32 s7, v254, 51
